# resid+norm epilogue: grid barrier between the partial sums and the normalisation replaced by a 4-workgroup rendezvous (write-through partials + counter)
# baseline (speedup 1.0000x reference)
.LBB0_532:
	v_and_b32_e32 v130, 64, v209
	s_lshl_b32 s6, s81, 8
	v_xor_b32_e32 v0, 16, v209
	v_add_u32_e32 v130, 64, v130
	s_add_i32 s6, s6, s47
	v_cmp_lt_i32_e32 vcc, v0, v130
	v_xor_b32_e32 v131, 32, v209
	s_lshl_b32 s0, s34, 5
	v_add_u32_e32 v194, s6, v145
	s_lshl_b32 s6, s84, 8
	v_cndmask_b32_e32 v0, v209, v0, vcc
	v_cmp_lt_i32_e32 vcc, v131, v130
	s_or_b32 s0, s6, s0
	v_ashrrev_i32_e32 v195, 31, v194
	v_cndmask_b32_e32 v130, v209, v131, vcc
	v_lshl_or_b32 v166, v144, 3, s0
	v_lshlrev_b32_e32 v172, 2, v130
	v_lshlrev_b64 v[130:131], 12, v[194:195]
	v_ashrrev_i32_e32 v167, 31, v166
	v_lshl_add_u64 v[130:131], s[16:17], 0, v[130:131]
	v_lshl_add_u64 v[138:139], v[166:167], 2, v[130:131]
	s_barrier
	v_lshlrev_b32_e32 v0, 2, v0
	v_mov_b32_e32 v251, v172
	v_cmp_eq_u32_e32 vcc, 0, v144
	v_lshlrev_b32_e32 v200, 12, v194
	v_lshl_add_u32 v200, v166, 2, v200
	s_lshl_b32 s6, s84, 2
	s_ashr_i32 s7, s6, 31
	s_lshl_b64 s[6:7], s[6:7], 2
	s_add_u32 s0, s22, s6
	s_addc_u32 s7, s23, s7
	s_lshl_b32 s6, s34, 2
	s_add_u32 s6, s0, s6
	s_addc_u32 s7, s7, 0
	v_readlane_b32 s28, v254, 39
	s_mov_b32 s98, s36
	s_mov_b32 s83, 0x800000
	v_readlane_b32 s29, v254, 40
	v_readlane_b32 s48, v254, 41
	s_mov_b64 s[34:35], s[50:51]
	v_readlane_b32 s49, v254, 42
	s_mov_b64 s[8:9], s[16:17]
	global_load_dwordx4 v[150:153], v200, s[8:9]
	global_load_dwordx4 v[146:149], v200, s[8:9] offset:16
	global_load_dwordx4 v[154:157], v200, s[8:9] offset:512
	global_load_dwordx4 v[158:161], v200, s[8:9] offset:528
	s_add_u32 s8, s16, 0x10000
	s_addc_u32 s9, s17, 0
	global_load_dwordx4 v[134:137], v200, s[8:9]
	global_load_dwordx4 v[130:133], v200, s[8:9] offset:16
	global_load_dwordx4 v[138:141], v200, s[8:9] offset:512
	global_load_dwordx4 v[142:145], v200, s[8:9] offset:528
	s_add_u32 s8, s16, 0x20000
	s_addc_u32 s9, s17, 0
	global_load_dwordx4 v[210:213], v200, s[8:9]
	global_load_dwordx4 v[214:217], v200, s[8:9] offset:16
	global_load_dwordx4 v[218:221], v200, s[8:9] offset:512
	global_load_dwordx4 v[222:225], v200, s[8:9] offset:528
	s_add_u32 s8, s16, 0x30000
	s_addc_u32 s9, s17, 0
	global_load_dwordx4 v[226:229], v200, s[8:9]
	global_load_dwordx4 v[230:233], v200, s[8:9] offset:16
	global_load_dwordx4 v[234:237], v200, s[8:9] offset:512
	global_load_dwordx4 v[238:241], v200, s[8:9] offset:528
	s_waitcnt vmcnt(12)
	v_pk_fma_f32 v[150:151], s[18:19], v[126:127], v[150:151]
	v_pk_fma_f32 v[152:153], s[24:25], v[128:129], v[152:153]
	v_pk_fma_f32 v[146:147], s[18:19], v[122:123], v[146:147]
	v_pk_fma_f32 v[148:149], s[24:25], v[124:125], v[148:149]
	v_pk_fma_f32 v[154:155], s[18:19], v[118:119], v[154:155]
	v_pk_fma_f32 v[156:157], s[24:25], v[120:121], v[156:157]
	v_pk_fma_f32 v[158:159], s[18:19], v[114:115], v[158:159]
	v_pk_fma_f32 v[160:161], s[24:25], v[116:117], v[160:161]
	v_mul_f32_e32 v202, v153, v153
	v_mul_f32_e32 v201, v151, v151
	v_fmac_f32_e32 v201, v150, v150
	v_fmac_f32_e32 v202, v152, v152
	v_add_f32_e32 v201, v201, v202
	v_mul_f32_e32 v206, v149, v149
	v_mul_f32_e32 v203, v147, v147
	v_fmac_f32_e32 v203, v146, v146
	v_fmac_f32_e32 v206, v148, v148
	v_add_f32_e32 v203, v203, v206
	v_add_f32_e32 v201, v201, v203
	v_mul_f32_e32 v206, v157, v157
	v_mul_f32_e32 v203, v155, v155
	v_fmac_f32_e32 v203, v154, v154
	v_fmac_f32_e32 v206, v156, v156
	v_add_f32_e32 v203, v203, v206
	v_mul_f32_e32 v206, v161, v161
	v_mul_f32_e32 v202, v159, v159
	v_fmac_f32_e32 v202, v158, v158
	v_fmac_f32_e32 v206, v160, v160
	v_add_f32_e32 v202, v202, v206
	v_add_f32_e32 v203, v203, v202
	v_add_f32_e32 v242, v201, v203
	s_add_u32 s8, s16, 0x80000
	s_addc_u32 s9, s17, 0
	global_load_dwordx4 v[114:117], v200, s[8:9]
	global_load_dwordx4 v[118:121], v200, s[8:9] offset:16
	global_load_dwordx4 v[122:125], v200, s[8:9] offset:512
	global_load_dwordx4 v[126:129], v200, s[8:9] offset:528
	s_waitcnt vmcnt(12)
	v_pk_fma_f32 v[134:135], s[18:19], v[110:111], v[134:135]
	v_pk_fma_f32 v[136:137], s[24:25], v[112:113], v[136:137]
	v_pk_fma_f32 v[130:131], s[18:19], v[106:107], v[130:131]
	v_pk_fma_f32 v[132:133], s[24:25], v[108:109], v[132:133]
	v_pk_fma_f32 v[138:139], s[18:19], v[102:103], v[138:139]
	v_pk_fma_f32 v[140:141], s[24:25], v[104:105], v[140:141]
	v_pk_fma_f32 v[142:143], s[18:19], v[98:99], v[142:143]
	v_pk_fma_f32 v[144:145], s[24:25], v[100:101], v[144:145]
	v_mul_f32_e32 v202, v137, v137
	v_mul_f32_e32 v201, v135, v135
	v_fmac_f32_e32 v201, v134, v134
	v_fmac_f32_e32 v202, v136, v136
	v_add_f32_e32 v201, v201, v202
	v_mul_f32_e32 v206, v133, v133
	v_mul_f32_e32 v203, v131, v131
	v_fmac_f32_e32 v203, v130, v130
	v_fmac_f32_e32 v206, v132, v132
	v_add_f32_e32 v203, v203, v206
	v_add_f32_e32 v201, v201, v203
	v_mul_f32_e32 v206, v141, v141
	v_mul_f32_e32 v203, v139, v139
	v_fmac_f32_e32 v203, v138, v138
	v_fmac_f32_e32 v206, v140, v140
	v_add_f32_e32 v203, v203, v206
	v_mul_f32_e32 v206, v145, v145
	v_mul_f32_e32 v202, v143, v143
	v_fmac_f32_e32 v202, v142, v142
	v_fmac_f32_e32 v206, v144, v144
	v_add_f32_e32 v202, v202, v206
	v_add_f32_e32 v203, v203, v202
	v_add_f32_e32 v243, v201, v203
	s_add_u32 s8, s16, 0x90000
	s_addc_u32 s9, s17, 0
	global_load_dwordx4 v[98:101], v200, s[8:9]
	global_load_dwordx4 v[102:105], v200, s[8:9] offset:16
	global_load_dwordx4 v[106:109], v200, s[8:9] offset:512
	global_load_dwordx4 v[110:113], v200, s[8:9] offset:528
	s_waitcnt vmcnt(12)
	v_pk_fma_f32 v[86:87], s[18:19], v[86:87], v[210:211]
	v_pk_fma_f32 v[88:89], s[24:25], v[88:89], v[212:213]
	v_pk_fma_f32 v[82:83], s[18:19], v[82:83], v[214:215]
	v_pk_fma_f32 v[84:85], s[24:25], v[84:85], v[216:217]
	v_pk_fma_f32 v[90:91], s[18:19], v[90:91], v[218:219]
	v_pk_fma_f32 v[92:93], s[24:25], v[92:93], v[220:221]
	v_pk_fma_f32 v[94:95], s[18:19], v[94:95], v[222:223]
	v_pk_fma_f32 v[96:97], s[24:25], v[96:97], v[224:225]
	v_mul_f32_e32 v202, v89, v89
	v_mul_f32_e32 v201, v87, v87
	v_fmac_f32_e32 v201, v86, v86
	v_fmac_f32_e32 v202, v88, v88
	v_add_f32_e32 v201, v201, v202
	v_mul_f32_e32 v206, v85, v85
	v_mul_f32_e32 v203, v83, v83
	v_fmac_f32_e32 v203, v82, v82
	v_fmac_f32_e32 v206, v84, v84
	v_add_f32_e32 v203, v203, v206
	v_add_f32_e32 v201, v201, v203
	v_mul_f32_e32 v206, v93, v93
	v_mul_f32_e32 v203, v91, v91
	v_fmac_f32_e32 v203, v90, v90
	v_fmac_f32_e32 v206, v92, v92
	v_add_f32_e32 v203, v203, v206
	v_mul_f32_e32 v206, v97, v97
	v_mul_f32_e32 v202, v95, v95
	v_fmac_f32_e32 v202, v94, v94
	v_fmac_f32_e32 v206, v96, v96
	v_add_f32_e32 v202, v202, v206
	v_add_f32_e32 v203, v203, v202
	v_add_f32_e32 v244, v201, v203
	s_add_u32 s8, s16, 0xa0000
	s_addc_u32 s9, s17, 0
	global_load_dwordx4 v[210:213], v200, s[8:9]
	global_load_dwordx4 v[214:217], v200, s[8:9] offset:16
	global_load_dwordx4 v[218:221], v200, s[8:9] offset:512
	global_load_dwordx4 v[222:225], v200, s[8:9] offset:528
	s_waitcnt vmcnt(12)
	v_pk_fma_f32 v[70:71], s[18:19], v[70:71], v[226:227]
	v_pk_fma_f32 v[72:73], s[24:25], v[72:73], v[228:229]
	v_pk_fma_f32 v[66:67], s[18:19], v[66:67], v[230:231]
	v_pk_fma_f32 v[68:69], s[24:25], v[68:69], v[232:233]
	v_pk_fma_f32 v[74:75], s[18:19], v[74:75], v[234:235]
	v_pk_fma_f32 v[76:77], s[24:25], v[76:77], v[236:237]
	v_pk_fma_f32 v[78:79], s[18:19], v[78:79], v[238:239]
	v_pk_fma_f32 v[80:81], s[24:25], v[80:81], v[240:241]
	v_mul_f32_e32 v202, v73, v73
	v_mul_f32_e32 v201, v71, v71
	v_fmac_f32_e32 v201, v70, v70
	v_fmac_f32_e32 v202, v72, v72
	v_add_f32_e32 v201, v201, v202
	v_mul_f32_e32 v206, v69, v69
	v_mul_f32_e32 v203, v67, v67
	v_fmac_f32_e32 v203, v66, v66
	v_fmac_f32_e32 v206, v68, v68
	v_add_f32_e32 v203, v203, v206
	v_add_f32_e32 v201, v201, v203
	v_mul_f32_e32 v206, v77, v77
	v_mul_f32_e32 v203, v75, v75
	v_fmac_f32_e32 v203, v74, v74
	v_fmac_f32_e32 v206, v76, v76
	v_add_f32_e32 v203, v203, v206
	v_mul_f32_e32 v206, v81, v81
	v_mul_f32_e32 v202, v79, v79
	v_fmac_f32_e32 v202, v78, v78
	v_fmac_f32_e32 v206, v80, v80
	v_add_f32_e32 v202, v202, v206
	v_add_f32_e32 v203, v203, v202
	v_add_f32_e32 v245, v201, v203
	s_add_u32 s8, s16, 0xb0000
	s_addc_u32 s9, s17, 0
	global_load_dwordx4 v[226:229], v200, s[8:9]
	global_load_dwordx4 v[230:233], v200, s[8:9] offset:16
	global_load_dwordx4 v[234:237], v200, s[8:9] offset:512
	global_load_dwordx4 v[238:241], v200, s[8:9] offset:528
	s_waitcnt vmcnt(12)
	v_pk_fma_f32 v[54:55], s[18:19], v[54:55], v[114:115]
	v_pk_fma_f32 v[56:57], s[24:25], v[56:57], v[116:117]
	v_pk_fma_f32 v[50:51], s[18:19], v[50:51], v[118:119]
	v_pk_fma_f32 v[52:53], s[24:25], v[52:53], v[120:121]
	v_pk_fma_f32 v[58:59], s[18:19], v[58:59], v[122:123]
	v_pk_fma_f32 v[60:61], s[24:25], v[60:61], v[124:125]
	v_pk_fma_f32 v[62:63], s[18:19], v[62:63], v[126:127]
	v_pk_fma_f32 v[64:65], s[24:25], v[64:65], v[128:129]
	v_mul_f32_e32 v202, v57, v57
	v_mul_f32_e32 v201, v55, v55
	v_fmac_f32_e32 v201, v54, v54
	v_fmac_f32_e32 v202, v56, v56
	v_add_f32_e32 v201, v201, v202
	v_mul_f32_e32 v206, v53, v53
	v_mul_f32_e32 v203, v51, v51
	v_fmac_f32_e32 v203, v50, v50
	v_fmac_f32_e32 v206, v52, v52
	v_add_f32_e32 v203, v203, v206
	v_add_f32_e32 v201, v201, v203
	v_mul_f32_e32 v206, v61, v61
	v_mul_f32_e32 v203, v59, v59
	v_fmac_f32_e32 v203, v58, v58
	v_fmac_f32_e32 v206, v60, v60
	v_add_f32_e32 v203, v203, v206
	v_mul_f32_e32 v206, v65, v65
	v_mul_f32_e32 v202, v63, v63
	v_fmac_f32_e32 v202, v62, v62
	v_fmac_f32_e32 v206, v64, v64
	v_add_f32_e32 v202, v202, v206
	v_add_f32_e32 v203, v203, v202
	v_add_f32_e32 v246, v201, v203
	s_waitcnt vmcnt(8)
	v_pk_fma_f32 v[38:39], s[18:19], v[38:39], v[98:99]
	v_pk_fma_f32 v[40:41], s[24:25], v[40:41], v[100:101]
	v_pk_fma_f32 v[34:35], s[18:19], v[34:35], v[102:103]
	v_pk_fma_f32 v[36:37], s[24:25], v[36:37], v[104:105]
	v_pk_fma_f32 v[42:43], s[18:19], v[42:43], v[106:107]
	v_pk_fma_f32 v[44:45], s[24:25], v[44:45], v[108:109]
	v_pk_fma_f32 v[46:47], s[18:19], v[46:47], v[110:111]
	v_pk_fma_f32 v[48:49], s[24:25], v[48:49], v[112:113]
	v_mul_f32_e32 v202, v41, v41
	v_mul_f32_e32 v201, v39, v39
	v_fmac_f32_e32 v201, v38, v38
	v_fmac_f32_e32 v202, v40, v40
	v_add_f32_e32 v201, v201, v202
	v_mul_f32_e32 v206, v37, v37
	v_mul_f32_e32 v203, v35, v35
	v_fmac_f32_e32 v203, v34, v34
	v_fmac_f32_e32 v206, v36, v36
	v_add_f32_e32 v203, v203, v206
	v_add_f32_e32 v201, v201, v203
	v_mul_f32_e32 v206, v45, v45
	v_mul_f32_e32 v203, v43, v43
	v_fmac_f32_e32 v203, v42, v42
	v_fmac_f32_e32 v206, v44, v44
	v_add_f32_e32 v203, v203, v206
	v_mul_f32_e32 v206, v49, v49
	v_mul_f32_e32 v202, v47, v47
	v_fmac_f32_e32 v202, v46, v46
	v_fmac_f32_e32 v206, v48, v48
	v_add_f32_e32 v202, v202, v206
	v_add_f32_e32 v203, v203, v202
	v_add_f32_e32 v247, v201, v203
	s_waitcnt vmcnt(4)
	v_pk_fma_f32 v[22:23], s[18:19], v[22:23], v[210:211]
	v_pk_fma_f32 v[24:25], s[24:25], v[24:25], v[212:213]
	v_pk_fma_f32 v[18:19], s[18:19], v[18:19], v[214:215]
	v_pk_fma_f32 v[20:21], s[24:25], v[20:21], v[216:217]
	v_pk_fma_f32 v[26:27], s[18:19], v[26:27], v[218:219]
	v_pk_fma_f32 v[28:29], s[24:25], v[28:29], v[220:221]
	v_pk_fma_f32 v[30:31], s[18:19], v[30:31], v[222:223]
	v_pk_fma_f32 v[32:33], s[24:25], v[32:33], v[224:225]
	v_mul_f32_e32 v202, v25, v25
	v_mul_f32_e32 v201, v23, v23
	v_fmac_f32_e32 v201, v22, v22
	v_fmac_f32_e32 v202, v24, v24
	v_add_f32_e32 v201, v201, v202
	v_mul_f32_e32 v206, v21, v21
	v_mul_f32_e32 v203, v19, v19
	v_fmac_f32_e32 v203, v18, v18
	v_fmac_f32_e32 v206, v20, v20
	v_add_f32_e32 v203, v203, v206
	v_add_f32_e32 v201, v201, v203
	v_mul_f32_e32 v206, v29, v29
	v_mul_f32_e32 v203, v27, v27
	v_fmac_f32_e32 v203, v26, v26
	v_fmac_f32_e32 v206, v28, v28
	v_add_f32_e32 v203, v203, v206
	v_mul_f32_e32 v206, v33, v33
	v_mul_f32_e32 v202, v31, v31
	v_fmac_f32_e32 v202, v30, v30
	v_fmac_f32_e32 v206, v32, v32
	v_add_f32_e32 v202, v202, v206
	v_add_f32_e32 v203, v203, v202
	v_add_f32_e32 v248, v201, v203
	s_waitcnt vmcnt(0)
	v_pk_fma_f32 v[6:7], s[18:19], v[6:7], v[226:227]
	v_pk_fma_f32 v[8:9], s[24:25], v[8:9], v[228:229]
	v_pk_fma_f32 v[2:3], s[18:19], v[2:3], v[230:231]
	v_pk_fma_f32 v[4:5], s[24:25], v[4:5], v[232:233]
	v_pk_fma_f32 v[10:11], s[18:19], v[10:11], v[234:235]
	v_pk_fma_f32 v[12:13], s[24:25], v[12:13], v[236:237]
	v_pk_fma_f32 v[14:15], s[18:19], v[14:15], v[238:239]
	v_pk_fma_f32 v[16:17], s[24:25], v[16:17], v[240:241]
	v_mul_f32_e32 v202, v9, v9
	v_mul_f32_e32 v201, v7, v7
	v_fmac_f32_e32 v201, v6, v6
	v_fmac_f32_e32 v202, v8, v8
	v_add_f32_e32 v201, v201, v202
	v_mul_f32_e32 v206, v5, v5
	v_mul_f32_e32 v203, v3, v3
	v_fmac_f32_e32 v203, v2, v2
	v_fmac_f32_e32 v206, v4, v4
	v_add_f32_e32 v203, v203, v206
	v_add_f32_e32 v201, v201, v203
	v_mul_f32_e32 v206, v13, v13
	v_mul_f32_e32 v203, v11, v11
	v_fmac_f32_e32 v203, v10, v10
	v_fmac_f32_e32 v206, v12, v12
	v_add_f32_e32 v203, v203, v206
	v_mul_f32_e32 v206, v17, v17
	v_mul_f32_e32 v202, v15, v15
	v_fmac_f32_e32 v202, v14, v14
	v_fmac_f32_e32 v206, v16, v16
	v_add_f32_e32 v202, v202, v206
	v_add_f32_e32 v203, v203, v202
	v_add_f32_e32 v249, v201, v203
	ds_bpermute_b32 v168, v0, v242
	ds_bpermute_b32 v169, v0, v243
	ds_bpermute_b32 v170, v0, v244
	ds_bpermute_b32 v171, v0, v245
	ds_bpermute_b32 v172, v0, v246
	ds_bpermute_b32 v173, v0, v247
	ds_bpermute_b32 v174, v0, v248
	ds_bpermute_b32 v175, v0, v249
	s_waitcnt lgkmcnt(0)
	v_add_f32_e32 v242, v242, v168
	v_add_f32_e32 v243, v243, v169
	v_add_f32_e32 v244, v244, v170
	v_add_f32_e32 v245, v245, v171
	v_add_f32_e32 v246, v246, v172
	v_add_f32_e32 v247, v247, v173
	v_add_f32_e32 v248, v248, v174
	v_add_f32_e32 v249, v249, v175
	ds_bpermute_b32 v168, v251, v242
	ds_bpermute_b32 v169, v251, v243
	ds_bpermute_b32 v170, v251, v244
	ds_bpermute_b32 v171, v251, v245
	ds_bpermute_b32 v172, v251, v246
	ds_bpermute_b32 v173, v251, v247
	ds_bpermute_b32 v174, v251, v248
	ds_bpermute_b32 v175, v251, v249
	v_lshlrev_b32_e32 v201, 6, v194
	v_add_u32_e32 v202, 0x2000, v201
	s_waitcnt lgkmcnt(0)
	v_add_f32_e32 v242, v242, v168
	v_add_f32_e32 v243, v243, v169
	v_add_f32_e32 v244, v244, v170
	v_add_f32_e32 v245, v245, v171
	v_add_f32_e32 v246, v246, v172
	v_add_f32_e32 v247, v247, v173
	v_add_f32_e32 v248, v248, v174
	v_add_f32_e32 v249, v249, v175
	s_and_saveexec_b64 s[8:9], vcc
	global_store_dword v201, v242, s[6:7] sc0 sc1
	global_store_dword v201, v243, s[6:7] offset:1024 sc0 sc1
	global_store_dword v201, v244, s[6:7] offset:2048 sc0 sc1
	global_store_dword v201, v245, s[6:7] offset:3072 sc0 sc1
	global_store_dword v202, v246, s[6:7] sc0 sc1
	global_store_dword v202, v247, s[6:7] offset:1024 sc0 sc1
	global_store_dword v202, v248, s[6:7] offset:2048 sc0 sc1
	global_store_dword v202, v249, s[6:7] offset:3072 sc0 sc1
	s_or_b64 exec, exec, s[8:9]
	s_waitcnt vmcnt(0)
	s_barrier
	v_readlane_b32 s8, v252, 4
	v_readlane_b32 s9, v252, 5
	v_readlane_b32 s0, v253, 31
	s_lshr_b32 s10, s47, 8
	s_lshl_b32 s0, s0, 7
	s_add_i32 s0, s0, s10
	s_add_i32 s0, s0, s81
	s_lshl_b32 s0, s0, 4
	s_add_u32 s10, s30, s0
	s_addc_u32 s11, s31, 0
	s_add_u32 s10, s10, 0x20000
	s_addc_u32 s11, s11, 0
	s_mov_b64 s[6:7], exec
	s_and_b64 exec, exec, s[8:9]
	s_cbranch_execz .Lrn_gb_done
	global_atomic_add v1, v208, s[10:11]
	s_mov_b32 s12, 0
.Lrn_gb_spin:
	global_load_dword v0, v1, s[10:11] sc1
	s_waitcnt vmcnt(0)
	v_cmp_gt_u32_e32 vcc, 4, v0
	s_cbranch_vccz .Lrn_gb_done
	s_sleep 1
	s_add_i32 s12, s12, 1
	s_cmp_lt_u32 s12, 0x4000
	s_cbranch_scc1 .Lrn_gb_spin
.Lrn_gb_done:
	s_mov_b64 exec, s[6:7]
	s_mov_b64 s[84:85], s[62:63]
	s_mov_b64 s[80:81], s[60:61]
	s_mov_b64 s[74:75], s[58:59]
	s_mov_b64 s[28:29], s[56:57]
	s_mov_b64 s[14:15], s[54:55]
	s_mov_b64 s[10:11], s[52:53]
	v_readlane_b32 s6, v254, 27
	v_readlane_b32 s7, v254, 28
	v_readlane_b32 s8, v253, 38
	v_readlane_b32 s9, v253, 39
	v_readlane_b32 s48, v253, 56
	v_readlane_b32 s49, v253, 57
	v_readlane_b32 s50, v254, 8
	v_readlane_b32 s51, v254, 9
	v_readlane_b32 s52, v254, 6
	v_readlane_b32 s53, v254, 7
	s_waitcnt lgkmcnt(0)
	s_barrier
	v_bfe_u32 v201, v204, 4, 2
	v_lshlrev_b32_e32 v202, 2, v166
	v_lshlrev_b32_e32 v203, 6, v194
	v_lshl_add_u32 v203, v201, 4, v203
	v_add_u32_e32 v206, 0x2000, v203
	v_xor_b32_e32 v207, 16, v209
	v_xor_b32_e32 v250, 32, v209
	v_lshlrev_b32_e32 v207, 2, v207
	v_lshlrev_b32_e32 v250, 2, v250
	global_load_dwordx4 v[210:213], v203, s[22:23] sc0 sc1
	global_load_dwordx4 v[214:217], v203, s[22:23] offset:1024 sc0 sc1
	global_load_dwordx4 v[218:221], v203, s[22:23] offset:2048 sc0 sc1
	global_load_dwordx4 v[222:225], v203, s[22:23] offset:3072 sc0 sc1
	global_load_dwordx4 v[226:229], v206, s[22:23] sc0 sc1
	global_load_dwordx4 v[230:233], v206, s[22:23] offset:1024 sc0 sc1
	global_load_dwordx4 v[234:237], v206, s[22:23] offset:2048 sc0 sc1
	global_load_dwordx4 v[238:241], v206, s[22:23] offset:3072 sc0 sc1
	global_load_dwordx4 v[122:125], v202, s[6:7]
	global_load_dwordx4 v[118:121], v202, s[6:7] offset:16
	global_load_dwordx4 v[110:113], v202, s[6:7] offset:512
	global_load_dwordx4 v[106:109], v202, s[6:7] offset:528
	s_and_b64 vcc, exec, s[8:9]
	s_cbranch_vccz .Lrn_g2_done
	global_load_dwordx4 v[114:117], v202, s[48:49]
	global_load_dwordx4 v[126:129], v202, s[48:49] offset:16
	global_load_dwordx4 v[98:101], v202, s[48:49] offset:512
	global_load_dwordx4 v[102:105], v202, s[48:49] offset:528
.Lrn_g2_done:
	v_lshlrev_b32_e32 v200, 12, v194
	v_lshl_add_u32 v200, v166, 2, v200
	v_lshlrev_b32_e32 v251, 11, v194
	v_lshl_add_u32 v251, v166, 1, v251
	v_readlane_b32 s6, v254, 10
	v_readlane_b32 s7, v254, 11
	s_waitcnt vmcnt(0)
	v_add_f32_e32 v210, v210, v211
	v_add_f32_e32 v212, v212, v213
	v_add_f32_e32 v242, v210, v212
	v_add_f32_e32 v214, v214, v215
	v_add_f32_e32 v216, v216, v217
	v_add_f32_e32 v243, v214, v216
	v_add_f32_e32 v218, v218, v219
	v_add_f32_e32 v220, v220, v221
	v_add_f32_e32 v244, v218, v220
	v_add_f32_e32 v222, v222, v223
	v_add_f32_e32 v224, v224, v225
	v_add_f32_e32 v245, v222, v224
	v_add_f32_e32 v226, v226, v227
	v_add_f32_e32 v228, v228, v229
	v_add_f32_e32 v246, v226, v228
	v_add_f32_e32 v230, v230, v231
	v_add_f32_e32 v232, v232, v233
	v_add_f32_e32 v247, v230, v232
	v_add_f32_e32 v234, v234, v235
	v_add_f32_e32 v236, v236, v237
	v_add_f32_e32 v248, v234, v236
	v_add_f32_e32 v238, v238, v239
	v_add_f32_e32 v240, v240, v241
	v_add_f32_e32 v249, v238, v240
	ds_bpermute_b32 v168, v207, v242
	ds_bpermute_b32 v169, v207, v243
	ds_bpermute_b32 v170, v207, v244
	ds_bpermute_b32 v171, v207, v245
	ds_bpermute_b32 v172, v207, v246
	ds_bpermute_b32 v173, v207, v247
	ds_bpermute_b32 v174, v207, v248
	ds_bpermute_b32 v175, v207, v249
	s_waitcnt lgkmcnt(0)
	v_add_f32_e32 v242, v242, v168
	v_add_f32_e32 v243, v243, v169
	v_add_f32_e32 v244, v244, v170
	v_add_f32_e32 v245, v245, v171
	v_add_f32_e32 v246, v246, v172
	v_add_f32_e32 v247, v247, v173
	v_add_f32_e32 v248, v248, v174
	v_add_f32_e32 v249, v249, v175
	ds_bpermute_b32 v168, v250, v242
	ds_bpermute_b32 v169, v250, v243
	ds_bpermute_b32 v170, v250, v244
	ds_bpermute_b32 v171, v250, v245
	ds_bpermute_b32 v172, v250, v246
	ds_bpermute_b32 v173, v250, v247
	ds_bpermute_b32 v174, v250, v248
	ds_bpermute_b32 v175, v250, v249
	s_waitcnt lgkmcnt(0)
	v_add_f32_e32 v242, v242, v168
	v_add_f32_e32 v243, v243, v169
	v_add_f32_e32 v244, v244, v170
	v_add_f32_e32 v245, v245, v171
	v_add_f32_e32 v246, v246, v172
	v_add_f32_e32 v247, v247, v173
	v_add_f32_e32 v248, v248, v174
	v_add_f32_e32 v249, v249, v175
	v_fmamk_f32 v242, v242, 0x3a800000, v205
	v_fmamk_f32 v243, v243, 0x3a800000, v205
	v_fmamk_f32 v244, v244, 0x3a800000, v205
	v_fmamk_f32 v245, v245, 0x3a800000, v205
	v_fmamk_f32 v246, v246, 0x3a800000, v205
	v_fmamk_f32 v247, v247, 0x3a800000, v205
	v_fmamk_f32 v248, v248, 0x3a800000, v205
	v_fmamk_f32 v249, v249, 0x3a800000, v205
	v_rsq_f32_e32 v242, v242
	v_rsq_f32_e32 v243, v243
	v_rsq_f32_e32 v244, v244
	v_rsq_f32_e32 v245, v245
	v_rsq_f32_e32 v246, v246
	v_rsq_f32_e32 v247, v247
	v_rsq_f32_e32 v248, v248
	v_rsq_f32_e32 v249, v249
	v_mov_b32_e32 v201, v200
	v_mov_b32_e32 v202, v251
	v_mov_b32_e32 v228, v242
	global_store_dwordx4 v201, v[150:153], s[52:53] nt
	global_store_dwordx4 v201, v[146:149], s[52:53] offset:16 nt
	global_store_dwordx4 v201, v[154:157], s[52:53] offset:512 nt
	global_store_dwordx4 v201, v[158:161], s[52:53] offset:528 nt
	v_pk_mul_f32 v[168:169], v[150:151], v[228:229] op_sel_hi:[1,0]
	v_pk_mul_f32 v[170:171], v[152:153], v[228:229] op_sel_hi:[1,0]
	v_pk_mul_f32 v[172:173], v[146:147], v[228:229] op_sel_hi:[1,0]
	v_pk_mul_f32 v[174:175], v[148:149], v[228:229] op_sel_hi:[1,0]
	v_pk_mul_f32 v[176:177], v[154:155], v[228:229] op_sel_hi:[1,0]
	v_pk_mul_f32 v[178:179], v[156:157], v[228:229] op_sel_hi:[1,0]
	v_pk_mul_f32 v[180:181], v[158:159], v[228:229] op_sel_hi:[1,0]
	v_pk_mul_f32 v[182:183], v[160:161], v[228:229] op_sel_hi:[1,0]
	v_pk_mul_f32 v[184:185], v[122:123], v[168:169]
	v_pk_mul_f32 v[186:187], v[124:125], v[170:171]
	v_pk_mul_f32 v[188:189], v[118:119], v[172:173]
	v_pk_mul_f32 v[190:191], v[120:121], v[174:175]
	v_pk_mul_f32 v[192:193], v[110:111], v[176:177]
	v_pk_mul_f32 v[194:195], v[112:113], v[178:179]
	v_pk_mul_f32 v[196:197], v[106:107], v[180:181]
	v_pk_mul_f32 v[198:199], v[108:109], v[182:183]
	v_cvt_pk_bf16_f32 v184, v184, v185
	v_cvt_pk_bf16_f32 v185, v186, v187
	v_cvt_pk_bf16_f32 v186, v188, v189
	v_cvt_pk_bf16_f32 v187, v190, v191
	global_store_dwordx4 v202, v[184:187], s[50:51]
	v_cvt_pk_bf16_f32 v192, v192, v193
	v_cvt_pk_bf16_f32 v193, v194, v195
	v_cvt_pk_bf16_f32 v194, v196, v197
	v_cvt_pk_bf16_f32 v195, v198, v199
	global_store_dwordx4 v202, v[192:195], s[50:51] offset:256
	s_and_b64 vcc, exec, s[8:9]
	s_cbranch_vccz .Lrn_nodual_0
	v_pk_mul_f32 v[210:211], v[114:115], v[168:169]
	v_pk_mul_f32 v[212:213], v[116:117], v[170:171]
	v_pk_mul_f32 v[214:215], v[126:127], v[172:173]
	v_pk_mul_f32 v[216:217], v[128:129], v[174:175]
	v_pk_mul_f32 v[218:219], v[98:99], v[176:177]
	v_pk_mul_f32 v[220:221], v[100:101], v[178:179]
	v_pk_mul_f32 v[222:223], v[102:103], v[180:181]
	v_pk_mul_f32 v[224:225], v[104:105], v[182:183]
	v_cvt_pk_bf16_f32 v210, v210, v211
	v_cvt_pk_bf16_f32 v211, v212, v213
	v_cvt_pk_bf16_f32 v212, v214, v215
	v_cvt_pk_bf16_f32 v213, v216, v217
	global_store_dwordx4 v202, v[210:213], s[6:7]
	v_cvt_pk_bf16_f32 v218, v218, v219
	v_cvt_pk_bf16_f32 v219, v220, v221
	v_cvt_pk_bf16_f32 v220, v222, v223
	v_cvt_pk_bf16_f32 v221, v224, v225
	global_store_dwordx4 v202, v[218:221], s[6:7] offset:256
.Lrn_nodual_0:
	v_add_u32_e32 v201, 0x10000, v200
	v_add_u32_e32 v202, 0x8000, v251
	v_mov_b32_e32 v228, v243
	global_store_dwordx4 v201, v[134:137], s[52:53] nt
	global_store_dwordx4 v201, v[130:133], s[52:53] offset:16 nt
	global_store_dwordx4 v201, v[138:141], s[52:53] offset:512 nt
	global_store_dwordx4 v201, v[142:145], s[52:53] offset:528 nt
	v_pk_mul_f32 v[168:169], v[134:135], v[228:229] op_sel_hi:[1,0]
	v_pk_mul_f32 v[170:171], v[136:137], v[228:229] op_sel_hi:[1,0]
	v_pk_mul_f32 v[172:173], v[130:131], v[228:229] op_sel_hi:[1,0]
	v_pk_mul_f32 v[174:175], v[132:133], v[228:229] op_sel_hi:[1,0]
	v_pk_mul_f32 v[176:177], v[138:139], v[228:229] op_sel_hi:[1,0]
	v_pk_mul_f32 v[178:179], v[140:141], v[228:229] op_sel_hi:[1,0]
	v_pk_mul_f32 v[180:181], v[142:143], v[228:229] op_sel_hi:[1,0]
	v_pk_mul_f32 v[182:183], v[144:145], v[228:229] op_sel_hi:[1,0]
	v_pk_mul_f32 v[184:185], v[122:123], v[168:169]
	v_pk_mul_f32 v[186:187], v[124:125], v[170:171]
	v_pk_mul_f32 v[188:189], v[118:119], v[172:173]
	v_pk_mul_f32 v[190:191], v[120:121], v[174:175]
	v_pk_mul_f32 v[192:193], v[110:111], v[176:177]
	v_pk_mul_f32 v[194:195], v[112:113], v[178:179]
	v_pk_mul_f32 v[196:197], v[106:107], v[180:181]
	v_pk_mul_f32 v[198:199], v[108:109], v[182:183]
	v_cvt_pk_bf16_f32 v184, v184, v185
	v_cvt_pk_bf16_f32 v185, v186, v187
	v_cvt_pk_bf16_f32 v186, v188, v189
	v_cvt_pk_bf16_f32 v187, v190, v191
	global_store_dwordx4 v202, v[184:187], s[50:51]
	v_cvt_pk_bf16_f32 v192, v192, v193
	v_cvt_pk_bf16_f32 v193, v194, v195
	v_cvt_pk_bf16_f32 v194, v196, v197
	v_cvt_pk_bf16_f32 v195, v198, v199
	global_store_dwordx4 v202, v[192:195], s[50:51] offset:256
	s_and_b64 vcc, exec, s[8:9]
	s_cbranch_vccz .Lrn_nodual_1
	v_pk_mul_f32 v[210:211], v[114:115], v[168:169]
	v_pk_mul_f32 v[212:213], v[116:117], v[170:171]
	v_pk_mul_f32 v[214:215], v[126:127], v[172:173]
	v_pk_mul_f32 v[216:217], v[128:129], v[174:175]
	v_pk_mul_f32 v[218:219], v[98:99], v[176:177]
	v_pk_mul_f32 v[220:221], v[100:101], v[178:179]
	v_pk_mul_f32 v[222:223], v[102:103], v[180:181]
	v_pk_mul_f32 v[224:225], v[104:105], v[182:183]
	v_cvt_pk_bf16_f32 v210, v210, v211
	v_cvt_pk_bf16_f32 v211, v212, v213
	v_cvt_pk_bf16_f32 v212, v214, v215
	v_cvt_pk_bf16_f32 v213, v216, v217
	global_store_dwordx4 v202, v[210:213], s[6:7]
	v_cvt_pk_bf16_f32 v218, v218, v219
	v_cvt_pk_bf16_f32 v219, v220, v221
	v_cvt_pk_bf16_f32 v220, v222, v223
	v_cvt_pk_bf16_f32 v221, v224, v225
	global_store_dwordx4 v202, v[218:221], s[6:7] offset:256
.Lrn_nodual_1:
	v_add_u32_e32 v201, 0x20000, v200
	v_add_u32_e32 v202, 0x10000, v251
	v_mov_b32_e32 v228, v244
	global_store_dwordx4 v201, v[86:89], s[52:53] nt
	global_store_dwordx4 v201, v[82:85], s[52:53] offset:16 nt
	global_store_dwordx4 v201, v[90:93], s[52:53] offset:512 nt
	global_store_dwordx4 v201, v[94:97], s[52:53] offset:528 nt
	v_pk_mul_f32 v[168:169], v[86:87], v[228:229] op_sel_hi:[1,0]
	v_pk_mul_f32 v[170:171], v[88:89], v[228:229] op_sel_hi:[1,0]
	v_pk_mul_f32 v[172:173], v[82:83], v[228:229] op_sel_hi:[1,0]
	v_pk_mul_f32 v[174:175], v[84:85], v[228:229] op_sel_hi:[1,0]
	v_pk_mul_f32 v[176:177], v[90:91], v[228:229] op_sel_hi:[1,0]
	v_pk_mul_f32 v[178:179], v[92:93], v[228:229] op_sel_hi:[1,0]
	v_pk_mul_f32 v[180:181], v[94:95], v[228:229] op_sel_hi:[1,0]
	v_pk_mul_f32 v[182:183], v[96:97], v[228:229] op_sel_hi:[1,0]
	v_pk_mul_f32 v[184:185], v[122:123], v[168:169]
	v_pk_mul_f32 v[186:187], v[124:125], v[170:171]
	v_pk_mul_f32 v[188:189], v[118:119], v[172:173]
	v_pk_mul_f32 v[190:191], v[120:121], v[174:175]
	v_pk_mul_f32 v[192:193], v[110:111], v[176:177]
	v_pk_mul_f32 v[194:195], v[112:113], v[178:179]
	v_pk_mul_f32 v[196:197], v[106:107], v[180:181]
	v_pk_mul_f32 v[198:199], v[108:109], v[182:183]
	v_cvt_pk_bf16_f32 v184, v184, v185
	v_cvt_pk_bf16_f32 v185, v186, v187
	v_cvt_pk_bf16_f32 v186, v188, v189
	v_cvt_pk_bf16_f32 v187, v190, v191
	global_store_dwordx4 v202, v[184:187], s[50:51]
	v_cvt_pk_bf16_f32 v192, v192, v193
	v_cvt_pk_bf16_f32 v193, v194, v195
	v_cvt_pk_bf16_f32 v194, v196, v197
	v_cvt_pk_bf16_f32 v195, v198, v199
	global_store_dwordx4 v202, v[192:195], s[50:51] offset:256
	s_and_b64 vcc, exec, s[8:9]
	s_cbranch_vccz .Lrn_nodual_2
	v_pk_mul_f32 v[210:211], v[114:115], v[168:169]
	v_pk_mul_f32 v[212:213], v[116:117], v[170:171]
	v_pk_mul_f32 v[214:215], v[126:127], v[172:173]
	v_pk_mul_f32 v[216:217], v[128:129], v[174:175]
	v_pk_mul_f32 v[218:219], v[98:99], v[176:177]
	v_pk_mul_f32 v[220:221], v[100:101], v[178:179]
	v_pk_mul_f32 v[222:223], v[102:103], v[180:181]
	v_pk_mul_f32 v[224:225], v[104:105], v[182:183]
	v_cvt_pk_bf16_f32 v210, v210, v211
	v_cvt_pk_bf16_f32 v211, v212, v213
	v_cvt_pk_bf16_f32 v212, v214, v215
	v_cvt_pk_bf16_f32 v213, v216, v217
	global_store_dwordx4 v202, v[210:213], s[6:7]
	v_cvt_pk_bf16_f32 v218, v218, v219
	v_cvt_pk_bf16_f32 v219, v220, v221
	v_cvt_pk_bf16_f32 v220, v222, v223
	v_cvt_pk_bf16_f32 v221, v224, v225
	global_store_dwordx4 v202, v[218:221], s[6:7] offset:256
.Lrn_nodual_2:
	v_add_u32_e32 v201, 0x30000, v200
	v_add_u32_e32 v202, 0x18000, v251
	v_mov_b32_e32 v228, v245
	global_store_dwordx4 v201, v[70:73], s[52:53] nt
	global_store_dwordx4 v201, v[66:69], s[52:53] offset:16 nt
	global_store_dwordx4 v201, v[74:77], s[52:53] offset:512 nt
	global_store_dwordx4 v201, v[78:81], s[52:53] offset:528 nt
	v_pk_mul_f32 v[168:169], v[70:71], v[228:229] op_sel_hi:[1,0]
	v_pk_mul_f32 v[170:171], v[72:73], v[228:229] op_sel_hi:[1,0]
	v_pk_mul_f32 v[172:173], v[66:67], v[228:229] op_sel_hi:[1,0]
	v_pk_mul_f32 v[174:175], v[68:69], v[228:229] op_sel_hi:[1,0]
	v_pk_mul_f32 v[176:177], v[74:75], v[228:229] op_sel_hi:[1,0]
	v_pk_mul_f32 v[178:179], v[76:77], v[228:229] op_sel_hi:[1,0]
	v_pk_mul_f32 v[180:181], v[78:79], v[228:229] op_sel_hi:[1,0]
	v_pk_mul_f32 v[182:183], v[80:81], v[228:229] op_sel_hi:[1,0]
	v_pk_mul_f32 v[184:185], v[122:123], v[168:169]
	v_pk_mul_f32 v[186:187], v[124:125], v[170:171]
	v_pk_mul_f32 v[188:189], v[118:119], v[172:173]
	v_pk_mul_f32 v[190:191], v[120:121], v[174:175]
	v_pk_mul_f32 v[192:193], v[110:111], v[176:177]
	v_pk_mul_f32 v[194:195], v[112:113], v[178:179]
	v_pk_mul_f32 v[196:197], v[106:107], v[180:181]
	v_pk_mul_f32 v[198:199], v[108:109], v[182:183]
	v_cvt_pk_bf16_f32 v184, v184, v185
	v_cvt_pk_bf16_f32 v185, v186, v187
	v_cvt_pk_bf16_f32 v186, v188, v189
	v_cvt_pk_bf16_f32 v187, v190, v191
	global_store_dwordx4 v202, v[184:187], s[50:51]
	v_cvt_pk_bf16_f32 v192, v192, v193
	v_cvt_pk_bf16_f32 v193, v194, v195
	v_cvt_pk_bf16_f32 v194, v196, v197
	v_cvt_pk_bf16_f32 v195, v198, v199
	global_store_dwordx4 v202, v[192:195], s[50:51] offset:256
	s_and_b64 vcc, exec, s[8:9]
	s_cbranch_vccz .Lrn_nodual_3
	v_pk_mul_f32 v[210:211], v[114:115], v[168:169]
	v_pk_mul_f32 v[212:213], v[116:117], v[170:171]
	v_pk_mul_f32 v[214:215], v[126:127], v[172:173]
	v_pk_mul_f32 v[216:217], v[128:129], v[174:175]
	v_pk_mul_f32 v[218:219], v[98:99], v[176:177]
	v_pk_mul_f32 v[220:221], v[100:101], v[178:179]
	v_pk_mul_f32 v[222:223], v[102:103], v[180:181]
	v_pk_mul_f32 v[224:225], v[104:105], v[182:183]
	v_cvt_pk_bf16_f32 v210, v210, v211
	v_cvt_pk_bf16_f32 v211, v212, v213
	v_cvt_pk_bf16_f32 v212, v214, v215
	v_cvt_pk_bf16_f32 v213, v216, v217
	global_store_dwordx4 v202, v[210:213], s[6:7]
	v_cvt_pk_bf16_f32 v218, v218, v219
	v_cvt_pk_bf16_f32 v219, v220, v221
	v_cvt_pk_bf16_f32 v220, v222, v223
	v_cvt_pk_bf16_f32 v221, v224, v225
	global_store_dwordx4 v202, v[218:221], s[6:7] offset:256
.Lrn_nodual_3:
	v_add_u32_e32 v201, 0x80000, v200
	v_add_u32_e32 v202, 0x40000, v251
	v_mov_b32_e32 v228, v246
	global_store_dwordx4 v201, v[54:57], s[52:53] nt
	global_store_dwordx4 v201, v[50:53], s[52:53] offset:16 nt
	global_store_dwordx4 v201, v[58:61], s[52:53] offset:512 nt
	global_store_dwordx4 v201, v[62:65], s[52:53] offset:528 nt
	v_pk_mul_f32 v[168:169], v[54:55], v[228:229] op_sel_hi:[1,0]
	v_pk_mul_f32 v[170:171], v[56:57], v[228:229] op_sel_hi:[1,0]
	v_pk_mul_f32 v[172:173], v[50:51], v[228:229] op_sel_hi:[1,0]
	v_pk_mul_f32 v[174:175], v[52:53], v[228:229] op_sel_hi:[1,0]
	v_pk_mul_f32 v[176:177], v[58:59], v[228:229] op_sel_hi:[1,0]
	v_pk_mul_f32 v[178:179], v[60:61], v[228:229] op_sel_hi:[1,0]
	v_pk_mul_f32 v[180:181], v[62:63], v[228:229] op_sel_hi:[1,0]
	v_pk_mul_f32 v[182:183], v[64:65], v[228:229] op_sel_hi:[1,0]
	v_pk_mul_f32 v[184:185], v[122:123], v[168:169]
	v_pk_mul_f32 v[186:187], v[124:125], v[170:171]
	v_pk_mul_f32 v[188:189], v[118:119], v[172:173]
	v_pk_mul_f32 v[190:191], v[120:121], v[174:175]
	v_pk_mul_f32 v[192:193], v[110:111], v[176:177]
	v_pk_mul_f32 v[194:195], v[112:113], v[178:179]
	v_pk_mul_f32 v[196:197], v[106:107], v[180:181]
	v_pk_mul_f32 v[198:199], v[108:109], v[182:183]
	v_cvt_pk_bf16_f32 v184, v184, v185
	v_cvt_pk_bf16_f32 v185, v186, v187
	v_cvt_pk_bf16_f32 v186, v188, v189
	v_cvt_pk_bf16_f32 v187, v190, v191
	global_store_dwordx4 v202, v[184:187], s[50:51]
	v_cvt_pk_bf16_f32 v192, v192, v193
	v_cvt_pk_bf16_f32 v193, v194, v195
	v_cvt_pk_bf16_f32 v194, v196, v197
	v_cvt_pk_bf16_f32 v195, v198, v199
	global_store_dwordx4 v202, v[192:195], s[50:51] offset:256
	s_and_b64 vcc, exec, s[8:9]
	s_cbranch_vccz .Lrn_nodual_4
	v_pk_mul_f32 v[210:211], v[114:115], v[168:169]
	v_pk_mul_f32 v[212:213], v[116:117], v[170:171]
	v_pk_mul_f32 v[214:215], v[126:127], v[172:173]
	v_pk_mul_f32 v[216:217], v[128:129], v[174:175]
	v_pk_mul_f32 v[218:219], v[98:99], v[176:177]
	v_pk_mul_f32 v[220:221], v[100:101], v[178:179]
	v_pk_mul_f32 v[222:223], v[102:103], v[180:181]
	v_pk_mul_f32 v[224:225], v[104:105], v[182:183]
	v_cvt_pk_bf16_f32 v210, v210, v211
	v_cvt_pk_bf16_f32 v211, v212, v213
	v_cvt_pk_bf16_f32 v212, v214, v215
	v_cvt_pk_bf16_f32 v213, v216, v217
	global_store_dwordx4 v202, v[210:213], s[6:7]
	v_cvt_pk_bf16_f32 v218, v218, v219
	v_cvt_pk_bf16_f32 v219, v220, v221
	v_cvt_pk_bf16_f32 v220, v222, v223
	v_cvt_pk_bf16_f32 v221, v224, v225
	global_store_dwordx4 v202, v[218:221], s[6:7] offset:256
.Lrn_nodual_4:
	v_add_u32_e32 v201, 0x90000, v200
	v_add_u32_e32 v202, 0x48000, v251
	v_mov_b32_e32 v228, v247
	global_store_dwordx4 v201, v[38:41], s[52:53] nt
	global_store_dwordx4 v201, v[34:37], s[52:53] offset:16 nt
	global_store_dwordx4 v201, v[42:45], s[52:53] offset:512 nt
	global_store_dwordx4 v201, v[46:49], s[52:53] offset:528 nt
	v_pk_mul_f32 v[168:169], v[38:39], v[228:229] op_sel_hi:[1,0]
	v_pk_mul_f32 v[170:171], v[40:41], v[228:229] op_sel_hi:[1,0]
	v_pk_mul_f32 v[172:173], v[34:35], v[228:229] op_sel_hi:[1,0]
	v_pk_mul_f32 v[174:175], v[36:37], v[228:229] op_sel_hi:[1,0]
	v_pk_mul_f32 v[176:177], v[42:43], v[228:229] op_sel_hi:[1,0]
	v_pk_mul_f32 v[178:179], v[44:45], v[228:229] op_sel_hi:[1,0]
	v_pk_mul_f32 v[180:181], v[46:47], v[228:229] op_sel_hi:[1,0]
	v_pk_mul_f32 v[182:183], v[48:49], v[228:229] op_sel_hi:[1,0]
	v_pk_mul_f32 v[184:185], v[122:123], v[168:169]
	v_pk_mul_f32 v[186:187], v[124:125], v[170:171]
	v_pk_mul_f32 v[188:189], v[118:119], v[172:173]
	v_pk_mul_f32 v[190:191], v[120:121], v[174:175]
	v_pk_mul_f32 v[192:193], v[110:111], v[176:177]
	v_pk_mul_f32 v[194:195], v[112:113], v[178:179]
	v_pk_mul_f32 v[196:197], v[106:107], v[180:181]
	v_pk_mul_f32 v[198:199], v[108:109], v[182:183]
	v_cvt_pk_bf16_f32 v184, v184, v185
	v_cvt_pk_bf16_f32 v185, v186, v187
	v_cvt_pk_bf16_f32 v186, v188, v189
	v_cvt_pk_bf16_f32 v187, v190, v191
	global_store_dwordx4 v202, v[184:187], s[50:51]
	v_cvt_pk_bf16_f32 v192, v192, v193
	v_cvt_pk_bf16_f32 v193, v194, v195
	v_cvt_pk_bf16_f32 v194, v196, v197
	v_cvt_pk_bf16_f32 v195, v198, v199
	global_store_dwordx4 v202, v[192:195], s[50:51] offset:256
	s_and_b64 vcc, exec, s[8:9]
	s_cbranch_vccz .Lrn_nodual_5
	v_pk_mul_f32 v[210:211], v[114:115], v[168:169]
	v_pk_mul_f32 v[212:213], v[116:117], v[170:171]
	v_pk_mul_f32 v[214:215], v[126:127], v[172:173]
	v_pk_mul_f32 v[216:217], v[128:129], v[174:175]
	v_pk_mul_f32 v[218:219], v[98:99], v[176:177]
	v_pk_mul_f32 v[220:221], v[100:101], v[178:179]
	v_pk_mul_f32 v[222:223], v[102:103], v[180:181]
	v_pk_mul_f32 v[224:225], v[104:105], v[182:183]
	v_cvt_pk_bf16_f32 v210, v210, v211
	v_cvt_pk_bf16_f32 v211, v212, v213
	v_cvt_pk_bf16_f32 v212, v214, v215
	v_cvt_pk_bf16_f32 v213, v216, v217
	global_store_dwordx4 v202, v[210:213], s[6:7]
	v_cvt_pk_bf16_f32 v218, v218, v219
	v_cvt_pk_bf16_f32 v219, v220, v221
	v_cvt_pk_bf16_f32 v220, v222, v223
	v_cvt_pk_bf16_f32 v221, v224, v225
	global_store_dwordx4 v202, v[218:221], s[6:7] offset:256
.Lrn_nodual_5:
	v_add_u32_e32 v201, 0xa0000, v200
	v_add_u32_e32 v202, 0x50000, v251
	v_mov_b32_e32 v228, v248
	global_store_dwordx4 v201, v[22:25], s[52:53] nt
	global_store_dwordx4 v201, v[18:21], s[52:53] offset:16 nt
	global_store_dwordx4 v201, v[26:29], s[52:53] offset:512 nt
	global_store_dwordx4 v201, v[30:33], s[52:53] offset:528 nt
	v_pk_mul_f32 v[168:169], v[22:23], v[228:229] op_sel_hi:[1,0]
	v_pk_mul_f32 v[170:171], v[24:25], v[228:229] op_sel_hi:[1,0]
	v_pk_mul_f32 v[172:173], v[18:19], v[228:229] op_sel_hi:[1,0]
	v_pk_mul_f32 v[174:175], v[20:21], v[228:229] op_sel_hi:[1,0]
	v_pk_mul_f32 v[176:177], v[26:27], v[228:229] op_sel_hi:[1,0]
	v_pk_mul_f32 v[178:179], v[28:29], v[228:229] op_sel_hi:[1,0]
	v_pk_mul_f32 v[180:181], v[30:31], v[228:229] op_sel_hi:[1,0]
	v_pk_mul_f32 v[182:183], v[32:33], v[228:229] op_sel_hi:[1,0]
	v_pk_mul_f32 v[184:185], v[122:123], v[168:169]
	v_pk_mul_f32 v[186:187], v[124:125], v[170:171]
	v_pk_mul_f32 v[188:189], v[118:119], v[172:173]
	v_pk_mul_f32 v[190:191], v[120:121], v[174:175]
	v_pk_mul_f32 v[192:193], v[110:111], v[176:177]
	v_pk_mul_f32 v[194:195], v[112:113], v[178:179]
	v_pk_mul_f32 v[196:197], v[106:107], v[180:181]
	v_pk_mul_f32 v[198:199], v[108:109], v[182:183]
	v_cvt_pk_bf16_f32 v184, v184, v185
	v_cvt_pk_bf16_f32 v185, v186, v187
	v_cvt_pk_bf16_f32 v186, v188, v189
	v_cvt_pk_bf16_f32 v187, v190, v191
	global_store_dwordx4 v202, v[184:187], s[50:51]
	v_cvt_pk_bf16_f32 v192, v192, v193
	v_cvt_pk_bf16_f32 v193, v194, v195
	v_cvt_pk_bf16_f32 v194, v196, v197
	v_cvt_pk_bf16_f32 v195, v198, v199
	global_store_dwordx4 v202, v[192:195], s[50:51] offset:256
	s_and_b64 vcc, exec, s[8:9]
	s_cbranch_vccz .Lrn_nodual_6
	v_pk_mul_f32 v[210:211], v[114:115], v[168:169]
	v_pk_mul_f32 v[212:213], v[116:117], v[170:171]
	v_pk_mul_f32 v[214:215], v[126:127], v[172:173]
	v_pk_mul_f32 v[216:217], v[128:129], v[174:175]
	v_pk_mul_f32 v[218:219], v[98:99], v[176:177]
	v_pk_mul_f32 v[220:221], v[100:101], v[178:179]
	v_pk_mul_f32 v[222:223], v[102:103], v[180:181]
	v_pk_mul_f32 v[224:225], v[104:105], v[182:183]
	v_cvt_pk_bf16_f32 v210, v210, v211
	v_cvt_pk_bf16_f32 v211, v212, v213
	v_cvt_pk_bf16_f32 v212, v214, v215
	v_cvt_pk_bf16_f32 v213, v216, v217
	global_store_dwordx4 v202, v[210:213], s[6:7]
	v_cvt_pk_bf16_f32 v218, v218, v219
	v_cvt_pk_bf16_f32 v219, v220, v221
	v_cvt_pk_bf16_f32 v220, v222, v223
	v_cvt_pk_bf16_f32 v221, v224, v225
	global_store_dwordx4 v202, v[218:221], s[6:7] offset:256
.Lrn_nodual_6:
	v_add_u32_e32 v201, 0xb0000, v200
	v_add_u32_e32 v202, 0x58000, v251
	v_mov_b32_e32 v228, v249
	global_store_dwordx4 v201, v[6:9], s[52:53] nt
	global_store_dwordx4 v201, v[2:5], s[52:53] offset:16 nt
	global_store_dwordx4 v201, v[10:13], s[52:53] offset:512 nt
	global_store_dwordx4 v201, v[14:17], s[52:53] offset:528 nt
	v_pk_mul_f32 v[168:169], v[6:7], v[228:229] op_sel_hi:[1,0]
	v_pk_mul_f32 v[170:171], v[8:9], v[228:229] op_sel_hi:[1,0]
	v_pk_mul_f32 v[172:173], v[2:3], v[228:229] op_sel_hi:[1,0]
	v_pk_mul_f32 v[174:175], v[4:5], v[228:229] op_sel_hi:[1,0]
	v_pk_mul_f32 v[176:177], v[10:11], v[228:229] op_sel_hi:[1,0]
	v_pk_mul_f32 v[178:179], v[12:13], v[228:229] op_sel_hi:[1,0]
	v_pk_mul_f32 v[180:181], v[14:15], v[228:229] op_sel_hi:[1,0]
	v_pk_mul_f32 v[182:183], v[16:17], v[228:229] op_sel_hi:[1,0]
	v_pk_mul_f32 v[184:185], v[122:123], v[168:169]
	v_pk_mul_f32 v[186:187], v[124:125], v[170:171]
	v_pk_mul_f32 v[188:189], v[118:119], v[172:173]
	v_pk_mul_f32 v[190:191], v[120:121], v[174:175]
	v_pk_mul_f32 v[192:193], v[110:111], v[176:177]
	v_pk_mul_f32 v[194:195], v[112:113], v[178:179]
	v_pk_mul_f32 v[196:197], v[106:107], v[180:181]
	v_pk_mul_f32 v[198:199], v[108:109], v[182:183]
	v_cvt_pk_bf16_f32 v184, v184, v185
	v_cvt_pk_bf16_f32 v185, v186, v187
	v_cvt_pk_bf16_f32 v186, v188, v189
	v_cvt_pk_bf16_f32 v187, v190, v191
	global_store_dwordx4 v202, v[184:187], s[50:51]
	v_cvt_pk_bf16_f32 v192, v192, v193
	v_cvt_pk_bf16_f32 v193, v194, v195
	v_cvt_pk_bf16_f32 v194, v196, v197
	v_cvt_pk_bf16_f32 v195, v198, v199
	global_store_dwordx4 v202, v[192:195], s[50:51] offset:256
	s_and_b64 vcc, exec, s[8:9]
	s_cbranch_vccz .Lrn_nodual_7
	v_pk_mul_f32 v[210:211], v[114:115], v[168:169]
	v_pk_mul_f32 v[212:213], v[116:117], v[170:171]
	v_pk_mul_f32 v[214:215], v[126:127], v[172:173]
	v_pk_mul_f32 v[216:217], v[128:129], v[174:175]
	v_pk_mul_f32 v[218:219], v[98:99], v[176:177]
	v_pk_mul_f32 v[220:221], v[100:101], v[178:179]
	v_pk_mul_f32 v[222:223], v[102:103], v[180:181]
	v_pk_mul_f32 v[224:225], v[104:105], v[182:183]
	v_cvt_pk_bf16_f32 v210, v210, v211
	v_cvt_pk_bf16_f32 v211, v212, v213
	v_cvt_pk_bf16_f32 v212, v214, v215
	v_cvt_pk_bf16_f32 v213, v216, v217
	global_store_dwordx4 v202, v[210:213], s[6:7]
	v_cvt_pk_bf16_f32 v218, v218, v219
	v_cvt_pk_bf16_f32 v219, v220, v221
	v_cvt_pk_bf16_f32 v220, v222, v223
	v_cvt_pk_bf16_f32 v221, v224, v225
	global_store_dwordx4 v202, v[218:221], s[6:7] offset:256
